# adds: HGRN prep reads raw bf16 values with ds_read_u16_d16_hi (no unpack VALU) and writes bf16 high halves with ds_write_b16_d16_hi
# baseline (speedup 1.0000x reference)
; #define LAS __attribute__((address_space(3)))
; __device__ __forceinline__ int otid() { int t = threadIdx.x; asm volatile("" : "+v"(t)); return t; }
; template <bool DRY> __device__ __forceinline__ void hgrn_unit(LAS unsigned char* lds, int b, int h, int vs, int layer, bf16_t* Pm, const float* lbraw) {
;     using namespace hg;
;     const int tid = otid(), lane = tid & 63; const int wid = __builtin_amdgcn_readfirstlane(tid >> 6);
;     const size_t tok0 = (size_t)b * SEQ;
;     const int kl = lane & 15, tq = lane >> 4, kch = 16 * wid + kl;
;     (void)layer; (void)lbraw;
;     const bf16_t* qsrc = Pm + (tok0 + 4 * tq) * PW + PC_HQ + h * 128 + (kch & ~1);
;     const bf16_t* fsrc = Pm + (tok0 + 4 * tq) * PW + PC_HF + h * 128 + (kch & ~1);
;     const bool isv = tid < 128; const int vv = tid & 31, vtq = (tid >> 5) & 3;
;     const bf16_t* vsrc = Pm + (tok0 + 4 * vtq) * PW + PC_HI + h * 128 + vs * 32 + (vv & ~1);
;     constexpr int NSTEP = SEQ / 16;
;     for (int i = tid; i < SB / 4; i += NTHREADS) ((LAS unsigned*)(lds + OFF_S + SB))[i] = 0u;
;     Raw ra, rb;
;     load_raw(ra, qsrc, fsrc, vsrc, 0, isv);
;     prep(ra, lds, lane, kch, tq, isv, vv, vtq);
;     load_raw(ra, qsrc, fsrc, vsrc, 1, isv); load_raw(rb, qsrc, fsrc, vsrc, 2, isv);
;     f32x16 sacc = {};
;     const int c16 = lane & 15, kq = lane >> 4, r32 = lane & 31, hh = lane >> 5;
;     __syncthreads();
.LBB0_615:
	s_or_b64 exec, exec, s[6:7]
	s_ashr_i32 s6, s22, 4
	s_ashr_i32 s7, s6, 31
	v_bfe_u32 v9, v3, 4, 2
	s_lshl_b64 s[14:15], s[6:7], 11
	v_lshlrev_b32_e32 v8, 2, v9
	v_or_b32_e32 v0, s14, v8
	v_mov_b64_e32 v[4:5], s[4:5]
	v_bfe_u32 v12, v3, 5, 2
	s_ashr_i32 s28, s10, 6
	s_mov_b32 s65, s28
	v_mad_u64_u32 v[0:1], s[6:7], v0, s24, v[4:5]
	s_lshl_b32 s10, s22, 5
	v_lshl_or_b32 v6, v12, 2, s14
	s_and_b32 s6, s10, 0x180
	v_mad_u64_u32 v[4:5], s[8:9], v6, s24, v[4:5]
	v_and_b32_e32 v7, 15, v3
	s_lshl_b32 s34, s28, 4
	v_mad_i32_i24 v1, s15, v240, v1
	s_lshl_b32 s6, s6, 1
	s_mov_b32 s7, s29
	v_mad_i32_i24 v5, s15, v240, v5
	v_lshl_add_u64 v[0:1], v[0:1], 0, s[6:7]
	v_bitop3_b32 v10, s34, -2, v7 bitop3:0xc8
	v_lshl_add_u64 v[4:5], v[4:5], 0, s[6:7]
	s_and_b32 s7, s10, 0x60
	v_ashrrev_i32_e32 v11, 31, v10
	s_lshl_b32 s8, s7, 1
	s_mul_i32 s41, s14, 0x1d40
	s_add_u32 s38, s4, s41
	s_addc_u32 s39, s5, 0
	s_add_u32 s38, s38, s6
	s_addc_u32 s39, s39, 0
	s_add_u32 s38, s38, 0xd00
	s_addc_u32 s39, s39, 0
	s_mov_b32 s9, s29
	v_and_b32_e32 v6, 30, v3
	v_lshl_add_u64 v[0:1], v[10:11], 1, v[0:1]
	v_lshl_add_u64 v[4:5], v[4:5], 0, s[8:9]
	v_lshlrev_b32_e32 v10, 1, v6
	v_mov_b32_e32 v11, v2
	s_movk_i32 s7, 0x1000
	v_lshl_add_u64 v[4:5], v[4:5], 0, v[10:11]
	v_add_co_u32_e32 v10, vcc, s7, v0
	v_cmp_eq_u32_e64 s[50:51], 3, v9
	s_nop 0
	v_addc_co_u32_e32 v11, vcc, 0, v1, vcc
	v_add_co_u32_e32 v14, vcc, s7, v4
	s_movk_i32 s7, 0x2000
	s_nop 0
	v_addc_co_u32_e32 v15, vcc, 0, v5, vcc
	v_add_co_u32_e32 v16, vcc, s7, v0
	s_movk_i32 s7, 0x3000
	s_nop 0
	v_addc_co_u32_e32 v17, vcc, 0, v1, vcc
	v_add_co_u32_e32 v18, vcc, s7, v4
	s_movk_i32 s7, 0x4000
	s_nop 0
	v_addc_co_u32_e32 v19, vcc, 0, v5, vcc
	v_add_co_u32_e32 v20, vcc, s7, v0
	s_nop 1
	v_addc_co_u32_e32 v21, vcc, 0, v1, vcc
	s_nop 0
	s_nop 0
	s_nop 0
	s_nop 0
	v_add_co_u32_e32 v10, vcc, s7, v4
	s_movk_i32 s7, 0x6000
	s_nop 0
	v_addc_co_u32_e32 v11, vcc, 0, v5, vcc
	v_add_co_u32_e32 v10, vcc, s7, v0
	s_nop 1
	v_addc_co_u32_e32 v11, vcc, 0, v1, vcc
	v_add_co_u32_e32 v18, vcc, s7, v4
	s_movk_i32 s7, 0x440
	s_nop 0
	v_addc_co_u32_e32 v19, vcc, 0, v5, vcc
	s_nop 0
	v_and_b32_e32 v19, 1, v3
	v_cmp_eq_u32_e64 s[44:45], 0, v19
	v_and_b32_e32 v11, 63, v3
	v_cmp_gt_u32_e64 s[46:47], 16, v11
	v_cmp_lt_u32_e64 s[48:49], 31, v11
	v_or_b32_e32 v10, s34, v7
	v_lshl_add_u32 v36, v10, 1, 0
	v_mad_u32_u24 v42, v9, s7, v36
	v_bfe_u32 v140, v234, 4, 2
	v_mul_u32_u24_e32 v136, 0x440, v140
	v_lshrrev_b32_e32 v140, 6, v234
	v_and_b32_e32 v141, 15, v234
	v_lshl_or_b32 v140, v140, 4, v141
	v_lshrrev_b32_e32 v140, 1, v140
	v_lshl_add_u32 v136, v140, 2, v136
	v_add_u32_e32 v136, 0xd400, v136
	v_and_b32_e32 v144, 1, v234
	v_lshl_add_u32 v144, v144, 1, v136
	v_bfe_u32 v140, v234, 5, 2
	v_and_b32_e32 v141, 31, v234
	v_lshrrev_b32_e32 v141, 1, v141
	v_lshlrev_b32_e32 v141, 2, v141
	v_lshl_add_u32 v137, v140, 8, v141
	v_add_u32_e32 v137, 0xf600, v137
	v_and_b32_e32 v140, 63, v234
	v_lshrrev_b32_e32 v141, 4, v140
	v_lshrrev_b32_e32 v142, 6, v234
	v_and_b32_e32 v143, 3, v142
	v_lshl_add_u32 v141, v143, 2, v141
	v_mul_u32_u24_e32 v138, 0x1d40, v141
	v_and_b32_e32 v141, 15, v140
	v_lshl_add_u32 v138, v141, 4, v138
	v_lshrrev_b32_e32 v142, 2, v142
	v_lshl_add_u32 v138, v142, 10, v138
	v_lshrrev_b32_e32 v141, 2, v140
	v_mul_u32_u24_e32 v139, 0x1d40, v141
	v_and_b32_e32 v141, 3, v140
	v_lshl_add_u32 v139, v141, 4, v139
	v_add_u32_e32 v139, 0x800, v139
	v_add_u32_e32 v139, s8, v139
	s_mul_i32 s64, s65, 0x440
	s_add_i32 s64, s64, 0xd400
	s_mov_b64 s[42:43], s[38:39]
	s_cmp_lg_u32 s65, 7
	s_cbranch_scc1 .Lhg_pro_nov
	s_add_i32 m0, s64, 0
	s_nop 0
	global_load_lds_dwordx4 v138, s[42:43]
	s_mov_b32 m0, 0xf600
	s_nop 0
	global_load_lds_dwordx4 v139, s[42:43]
	s_add_u32 s42, s42, 0x1d400
	s_addc_u32 s43, s43, 0
	s_add_i32 m0, s64, 9792
	s_nop 0
	global_load_lds_dwordx4 v138, s[42:43]
	s_mov_b32 m0, 0x11c40
	s_nop 0
	global_load_lds_dwordx4 v139, s[42:43]
	s_add_u32 s42, s42, 0x1d400
	s_addc_u32 s43, s43, 0
	s_add_i32 m0, s64, 19584
	s_nop 0
	global_load_lds_dwordx4 v138, s[42:43]
	s_mov_b32 m0, 0x14280
	s_nop 0
	global_load_lds_dwordx4 v139, s[42:43]
	s_add_u32 s42, s42, 0x1d400
	s_addc_u32 s43, s43, 0
	s_add_i32 m0, s64, 29376
	s_nop 0
	global_load_lds_dwordx4 v138, s[42:43]
	s_mov_b32 m0, 0x168c0
	s_nop 0
	global_load_lds_dwordx4 v139, s[42:43]
	s_waitcnt vmcnt(4)
	s_branch .Lhg_pro_done

; #define LAS __attribute__((address_space(3)))
; __device__ __forceinline__ unsigned cvtpk(float lo, float hi) { f32x2_t v = {lo, hi}; bf16x2_t b = __builtin_convertvector(v, bf16x2_t); return __builtin_bit_cast(unsigned, b); }
; __device__ __forceinline__ void prep(const Raw& Rin, LAS unsigned char* buf, int lane, int kch, int tq, bool isv, int vv, int vtq) {
;     Raw R = Rin; const bool kodd = kch & 1, vodd = vv & 1;
; #pragma unroll
;     for (int i = 0; i < 4; ++i) { asm volatile("" : "+v"(R.q[i])); asm volatile("" : "+v"(R.f[i])); asm volatile("" : "+v"(R.v[i])); }
;     float qv[4], kk[4], c[4]; float run = 0.f;
; #pragma unroll
;     for (int i = 0; i < 4; ++i) {
;         qv[i] = __uint_as_float(kodd ? (R.q[i] & 0xffff0000u) : (R.q[i] << 16));
;         const float l2 = __uint_as_float(kodd ? (R.f[i] & 0xffff0000u) : (R.f[i] << 16));
;         kk[i] = 1.f - __builtin_amdgcn_exp2f(l2);
;         run += l2; c[i] = run;
;     }
;     const float p1 = __shfl(run, (lane - 16) & 63), p2 = __shfl(run, (lane - 32) & 63), p3 = __shfl(run, (lane - 48) & 63);
;     const float off = (tq >= 1 ? p1 : 0.f) + (tq >= 2 ? p2 : 0.f) + (tq >= 3 ? p3 : 0.f);
;     const float btot = __shfl(off + run, 48 + (lane & 15));
;     unsigned short kf[4];
; #pragma unroll
;     for (int i = 0; i < 4; ++i) {
;         const float bt = off + c[i];
;         const float qf = qv[i] * __builtin_amdgcn_exp2f(bt), kfv = kk[i] * __builtin_amdgcn_exp2f(-bt);
;         const unsigned pk = cvtpk(qf, kfv);
;         *(LAS unsigned short*)(buf + OFF_QF + (4 * tq + i) * STR + kch * 2) = (unsigned short)(pk & 0xffffu);
;         kf[i] = (unsigned short)(pk >> 16);
;         *(LAS unsigned short*)(buf + OFF_KF + (4 * tq + i) * STR + kch * 2) = kf[i];
;     }
;     *(LAS u32x2*)(buf + OFF_KFT + kch * 32 + tq * 8) = (u32x2){(unsigned)kf[0] | ((unsigned)kf[1] << 16), (unsigned)kf[2] | ((unsigned)kf[3] << 16)};
;     if (tq == 0) *(LAS float*)(buf + OFF_D + kch * 4) = __builtin_amdgcn_exp2f(btot);
;     if (isv) { unsigned v0 = vodd ? R.v[0] >> 16 : R.v[0] & 0xffffu, v1 = vodd ? R.v[1] >> 16 : R.v[1] & 0xffffu, v2 = vodd ? R.v[2] >> 16 : R.v[2] & 0xffffu, v3 = vodd ? R.v[3] >> 16 : R.v[3] & 0xffffu;
;         *(LAS u32x2*)(buf + OFF_VT + vv * 32 + vtq * 8) = (u32x2){v0 | (v1 << 16), v2 | (v3 << 16)}; }
; }
.Lhg_nov_a:
	s_add_i32 s41, s7, 1
	s_and_b32 s41, s41, 3
	s_mul_i32 s41, s41, 9792
	v_add_u32_e32 v140, s41, v144
	v_add_u32_e32 v141, s41, v137
	v_mov_b32_e32 v0, 0
	v_mov_b32_e32 v1, 0
	v_mov_b32_e32 v3, 0
	v_mov_b32_e32 v56, 0
	v_mov_b32_e32 v78, 0
	v_mov_b32_e32 v62, 0
	v_mov_b32_e32 v84, 0
	v_mov_b32_e32 v88, 0
	ds_read_u16_d16_hi v0, v140 offset:4352
	ds_read_u16_d16_hi v1, v140 offset:4608
	ds_read_u16_d16_hi v3, v140 offset:4864
	ds_read_u16_d16_hi v56, v140 offset:5120
	ds_read_u16_d16_hi v78, v140
	ds_read_u16_d16_hi v62, v140 offset:256
	ds_read_u16_d16_hi v84, v140 offset:512
	ds_read_u16_d16_hi v88, v140 offset:768
	ds_read_b32 v40, v141
	ds_read_b32 v41, v141 offset:64
	ds_read_b32 v53, v141 offset:128
	ds_read_b32 v64, v141 offset:192
	s_waitcnt lgkmcnt(8)
	v_exp_f32_e32 v81, v0
	v_exp_f32_e32 v83, v1
	v_exp_f32_e32 v87, v3
	v_exp_f32_e32 v54, v56
	v_add_f32_e32 v1, v0, v1
	v_add_f32_e32 v3, v1, v3
	v_add_f32_e32 v63, v3, v56
	v_sub_f32_e32 v81, 1.0, v81
	v_sub_f32_e32 v83, 1.0, v83
	v_sub_f32_e32 v87, 1.0, v87
	ds_bpermute_b32 v69, v32, v63
	ds_bpermute_b32 v71, v33, v63
	ds_bpermute_b32 v52, v34, v63
	s_waitcnt lgkmcnt(2)
	v_cndmask_b32_e64 v56, v69, 0, s[46:47]
	s_waitcnt lgkmcnt(1)
	v_cndmask_b32_e64 v69, 0, v71, s[48:49]
	v_add_f32_e32 v56, v56, v69
	s_waitcnt lgkmcnt(0)
	v_cndmask_b32_e64 v52, 0, v52, s[50:51]
	v_add_f32_e32 v52, v56, v52
	v_add_f32_e32 v0, v0, v52
	v_exp_f32_e32 v80, v0
	v_exp_f32_e64 v79, -v0
	v_add_f32_e32 v1, v1, v52
	v_sub_f32_e32 v91, 1.0, v54
	v_add_f32_e32 v54, v63, v52
	v_exp_f32_e32 v82, v1
	v_exp_f32_e64 v63, -v1
	v_add_f32_e32 v3, v3, v52
	v_pk_mul_f32 v[78:79], v[80:81], v[78:79]
	v_exp_f32_e32 v86, v3
	v_exp_f32_e64 v85, -v3
	v_cvt_pk_bf16_f32 v56, v78, v79
	v_exp_f32_e32 v90, v54
	v_exp_f32_e64 v89, -v54
	v_add_u32_e32 v69, v26, v43
	v_pk_mul_f32 v[62:63], v[82:83], v[62:63]
	ds_bpermute_b32 v0, v35, v54
	ds_write_b16_d16_hi v69, v56 offset:18688
	v_cvt_pk_bf16_f32 v1, v62, v63
	v_pk_mul_f32 v[62:63], v[86:87], v[84:85]
	ds_write_b16_d16_hi v69, v1 offset:18960
	v_cvt_pk_bf16_f32 v3, v62, v63
	v_pk_mul_f32 v[78:79], v[90:91], v[88:89]
	ds_write_b16 v69, v1 offset:14608
	v_perm_b32 v62, v1, v56, s17
	v_cvt_pk_bf16_f32 v1, v78, v79
	ds_write_b16_d16_hi v69, v3 offset:19232
	ds_write_b16 v69, v1 offset:15152
	v_lshrrev_b32_e32 v52, 16, v1
	v_perm_b32 v63, v1, v3, s17
	v_add_u32_e32 v1, v27, v37
	ds_write_b16 v69, v56 offset:14336
	ds_write_b16 v69, v3 offset:14880
	ds_write_b16 v69, v52 offset:19504
	ds_write_b64 v1, v[62:63] offset:23040
	s_and_saveexec_b64 s[14:15], s[46:47]
	s_cbranch_execz .LBB0_627
	s_waitcnt lgkmcnt(9)
	v_exp_f32_e32 v0, v0
	v_add_u32_e32 v1, v27, v45
	ds_write_b32 v1, v0 offset:28160

; #define LAS __attribute__((address_space(3)))
; __device__ __forceinline__ unsigned cvtpk(float lo, float hi) { f32x2_t v = {lo, hi}; bf16x2_t b = __builtin_convertvector(v, bf16x2_t); return __builtin_bit_cast(unsigned, b); }
; __device__ __forceinline__ void prep(const Raw& Rin, LAS unsigned char* buf, int lane, int kch, int tq, bool isv, int vv, int vtq) {
;     Raw R = Rin; const bool kodd = kch & 1, vodd = vv & 1;
; #pragma unroll
;     for (int i = 0; i < 4; ++i) { asm volatile("" : "+v"(R.q[i])); asm volatile("" : "+v"(R.f[i])); asm volatile("" : "+v"(R.v[i])); }
;     float qv[4], kk[4], c[4]; float run = 0.f;
; #pragma unroll
;     for (int i = 0; i < 4; ++i) {
;         qv[i] = __uint_as_float(kodd ? (R.q[i] & 0xffff0000u) : (R.q[i] << 16));
;         const float l2 = __uint_as_float(kodd ? (R.f[i] & 0xffff0000u) : (R.f[i] << 16));
;         kk[i] = 1.f - __builtin_amdgcn_exp2f(l2);
;         run += l2; c[i] = run;
;     }
;     const float p1 = __shfl(run, (lane - 16) & 63), p2 = __shfl(run, (lane - 32) & 63), p3 = __shfl(run, (lane - 48) & 63);
;     const float off = (tq >= 1 ? p1 : 0.f) + (tq >= 2 ? p2 : 0.f) + (tq >= 3 ? p3 : 0.f);
;     const float btot = __shfl(off + run, 48 + (lane & 15));
;     unsigned short kf[4];
; #pragma unroll
;     for (int i = 0; i < 4; ++i) {
;         const float bt = off + c[i];
;         const float qf = qv[i] * __builtin_amdgcn_exp2f(bt), kfv = kk[i] * __builtin_amdgcn_exp2f(-bt);
;         const unsigned pk = cvtpk(qf, kfv);
;         *(LAS unsigned short*)(buf + OFF_QF + (4 * tq + i) * STR + kch * 2) = (unsigned short)(pk & 0xffffu);
;         kf[i] = (unsigned short)(pk >> 16);
;         *(LAS unsigned short*)(buf + OFF_KF + (4 * tq + i) * STR + kch * 2) = kf[i];
;     }
;     *(LAS u32x2*)(buf + OFF_KFT + kch * 32 + tq * 8) = (u32x2){(unsigned)kf[0] | ((unsigned)kf[1] << 16), (unsigned)kf[2] | ((unsigned)kf[3] << 16)};
;     if (tq == 0) *(LAS float*)(buf + OFF_D + kch * 4) = __builtin_amdgcn_exp2f(btot);
;     if (isv) { unsigned v0 = vodd ? R.v[0] >> 16 : R.v[0] & 0xffffu, v1 = vodd ? R.v[1] >> 16 : R.v[1] & 0xffffu, v2 = vodd ? R.v[2] >> 16 : R.v[2] & 0xffffu, v3 = vodd ? R.v[3] >> 16 : R.v[3] & 0xffffu;
;         *(LAS u32x2*)(buf + OFF_VT + vv * 32 + vtq * 8) = (u32x2){v0 | (v1 << 16), v2 | (v3 << 16)}; }
; }
.Lhg_nov_b:
	s_add_i32 s41, s7, 2
	s_and_b32 s41, s41, 3
	s_mul_i32 s41, s41, 9792
	v_add_u32_e32 v140, s41, v144
	v_add_u32_e32 v141, s41, v137
	v_mov_b32_e32 v0, 0
	v_mov_b32_e32 v1, 0
	v_mov_b32_e32 v3, 0
	v_mov_b32_e32 v72, 0
	v_mov_b32_e32 v66, 0
	v_mov_b32_e32 v82, 0
	v_mov_b32_e32 v74, 0
	v_mov_b32_e32 v76, 0
	ds_read_u16_d16_hi v0, v140 offset:4352
	ds_read_u16_d16_hi v1, v140 offset:4608
	ds_read_u16_d16_hi v3, v140 offset:4864
	ds_read_u16_d16_hi v72, v140 offset:5120
	ds_read_u16_d16_hi v66, v140
	ds_read_u16_d16_hi v82, v140 offset:256
	ds_read_u16_d16_hi v74, v140 offset:512
	ds_read_u16_d16_hi v76, v140 offset:768
	ds_read_b32 v42, v141
	ds_read_b32 v55, v141 offset:64
	ds_read_b32 v65, v141 offset:128
	ds_read_b32 v70, v141 offset:192
	s_waitcnt lgkmcnt(8)
	v_exp_f32_e32 v81, v0
	v_exp_f32_e32 v85, v1
	v_exp_f32_e32 v87, v3
	v_exp_f32_e32 v68, v72
	v_add_f32_e32 v1, v0, v1
	v_add_f32_e32 v3, v1, v3
	v_add_f32_e32 v75, v3, v72
	v_sub_f32_e32 v81, 1.0, v81
	v_sub_f32_e32 v85, 1.0, v85
	v_sub_f32_e32 v87, 1.0, v87
	ds_bpermute_b32 v77, v32, v75
	ds_bpermute_b32 v79, v33, v75
	ds_bpermute_b32 v67, v34, v75
	s_waitcnt lgkmcnt(2)
	v_cndmask_b32_e64 v72, v77, 0, s[46:47]
	s_waitcnt lgkmcnt(1)
	v_cndmask_b32_e64 v77, 0, v79, s[48:49]
	v_add_f32_e32 v72, v72, v77
	s_waitcnt lgkmcnt(0)
	v_cndmask_b32_e64 v67, 0, v67, s[50:51]
	v_add_f32_e32 v72, v72, v67
	v_add_f32_e32 v0, v0, v72
	v_exp_f32_e32 v80, v0
	v_exp_f32_e64 v67, -v0
	v_add_f32_e32 v1, v1, v72
	v_exp_f32_e32 v84, v1
	v_exp_f32_e64 v83, -v1
	v_sub_f32_e32 v89, 1.0, v68
	v_add_f32_e32 v68, v75, v72
	v_add_f32_e32 v3, v3, v72
	v_pk_mul_f32 v[66:67], v[80:81], v[66:67]
	v_exp_f32_e32 v86, v3
	v_exp_f32_e64 v75, -v3
	v_exp_f32_e32 v88, v68
	v_exp_f32_e64 v77, -v68
	v_cvt_pk_bf16_f32 v79, v66, v67
	ds_bpermute_b32 v0, v35, v68
	v_add_u32_e32 v80, v36, v43
	v_pk_mul_f32 v[66:67], v[84:85], v[82:83]
	ds_write_b16_d16_hi v80, v79 offset:4352
	v_cvt_pk_bf16_f32 v1, v66, v67
	v_pk_mul_f32 v[66:67], v[86:87], v[74:75]
	v_pk_mul_f32 v[74:75], v[88:89], v[76:77]
	ds_write_b16 v80, v1 offset:272
	ds_write_b16_d16_hi v80, v1 offset:4624
	v_cvt_pk_bf16_f32 v3, v66, v67
	v_perm_b32 v66, v1, v79, s17
	v_cvt_pk_bf16_f32 v1, v74, v75
	v_lshrrev_b32_e32 v68, 16, v1
	ds_write_b16 v80, v79
	ds_write_b16 v80, v3 offset:544
	ds_write_b16_d16_hi v80, v3 offset:4896
	ds_write_b16 v80, v1 offset:816
	v_perm_b32 v67, v1, v3, s17
	ds_write_b16 v80, v68 offset:5168
	ds_write_b64 v38, v[66:67] offset:8704
	s_and_saveexec_b64 s[14:15], s[46:47]
	s_cbranch_execz .LBB0_638
	s_waitcnt lgkmcnt(9)
	v_exp_f32_e32 v0, v0
	v_add_u32_e32 v1, v27, v45
	ds_write_b32 v1, v0 offset:13824
